# baseline (speedup 1.0000x reference)
; template <bool BOUNDARY, bool Q0, bool Q1>
; __device__ __forceinline__ void attn_tile(const bf16* Ks, const bf16* Vt, const bf16x8 (&Qf)[2][2], const uint32_t (&vm)[2],
;                                           float (&m)[2], float (&l)[2], f32x4 (&O)[4][2], int fr, int fq) {
;   f32x4 S[4][2];
; #pragma unroll
;   for (int kt = 0; kt < 4; ++kt) {
;     S[kt][0] = f32x4{0.f, 0.f, 0.f, 0.f};
;     S[kt][1] = f32x4{0.f, 0.f, 0.f, 0.f};
; #pragma unroll
;     for (int ks = 0; ks < 2; ++ks) {
;       const bf16x8 kf = *(const bf16x8*)(Ks + (16 * kt + fr) * KS_LD + 32 * ks + 8 * fq);
;       if (Q0) S[kt][0] = __builtin_amdgcn_mfma_f32_16x16x32_bf16(kf, Qf[0][ks], S[kt][0], 0, 0, 0);
;       if (Q1) S[kt][1] = __builtin_amdgcn_mfma_f32_16x16x32_bf16(kf, Qf[1][ks], S[kt][1], 0, 0, 0);
;     }
;   }
; #pragma unroll
;   for (int qt = 0; qt < 2; ++qt) {
;     if ((qt == 0 && !Q0) || (qt == 1 && !Q1)) continue;
;     float mx, mxu;
;     if (BOUNDARY) {
;       mx = m[qt];
; #pragma unroll
;       for (int kt = 0; kt < 4; ++kt)
; #pragma unroll
;         for (int j = 0; j < 4; ++j) {
;           const float s2 = S[kt][qt][j];
;           if ((vm[qt] >> (kt * 4 + j)) & 1u) mx = fmaxf(mx, s2);
;         }
;       mx = fmaxf(mx, __shfl_xor(mx, 16));
;       mx = fmaxf(mx, __shfl_xor(mx, 32));
;       mxu = mx;
;     } else {
;       float rm = -3.0e38f;
; #pragma unroll
;       for (int kt = 0; kt < 4; ++kt)
; #pragma unroll
;         for (int j = 0; j < 4; ++j) {
;           rm = fmaxf(rm, S[kt][qt][j]);
;         }
;       rm = fmaxf(rm, __shfl_xor(rm, 16));
;       rm = fmaxf(rm, __shfl_xor(rm, 32));
;       const bool rv = vm[qt] != 0u;
;       mx = rv ? fmaxf(m[qt], rm) : m[qt];
;       mxu = rv ? mx : 3.0e38f;
;     }
;     const float alpha = __builtin_amdgcn_exp2f(m[qt] - mx);
;     m[qt] = mx;
;     float ls = 0.f;
; #pragma unroll
;     for (int kt = 0; kt < 4; ++kt)
; #pragma unroll
;       for (int j = 0; j < 4; ++j) {
;         float pv;
;         if (BOUNDARY) pv = ((vm[qt] >> (kt * 4 + j)) & 1u) ? __builtin_amdgcn_exp2f(S[kt][qt][j] - mxu) : 0.f;
;         else pv = __builtin_amdgcn_exp2f(S[kt][qt][j] - mxu);
;         S[kt][qt][j] = pv;
;         ls += pv;
;       }
;     l[qt] = l[qt] * alpha + ls;
; #pragma unroll
;     for (int dt = 0; dt < 4; ++dt) {
.LBB0_690:
	s_cmp_lg_u32 s37, s62
	s_cselect_b64 s[2:3], -1, 0
	s_cmp_lg_u32 s37, s36
	v_mul_lo_u32 v235, v161, s40
	s_cselect_b64 s[4:5], -1, 0
	s_and_b64 s[4:5], s[2:3], s[4:5]
	v_add_u32_e32 v88, v235, v152
	s_mov_b64 s[2:3], -1
	s_and_b64 vcc, exec, s[4:5]
	v_lshlrev_b32_e32 v236, 1, v233
	v_add_u32_e32 v242, v88, v230
	v_add_u32_e32 v241, v88, v163
	s_cbranch_vccz .LBB0_693
	ds_read_b128 v[88:91], v242
	ds_read_b128 v[128:131], v242 offset:64
	s_waitcnt lgkmcnt(1)
	v_mfma_f32_16x16x32_bf16 v[124:127], v[88:91], v[0:3], 0
	ds_read_b128 v[132:135], v241 offset:64
	ds_read_b128 v[144:147], v241 offset:2368
	ds_read_b128 v[174:177], v241 offset:4672
	v_mfma_f32_16x16x32_bf16 v[88:91], v[88:91], v[8:11], 0
	s_waitcnt lgkmcnt(3)
	v_mfma_f32_16x16x32_bf16 v[140:143], v[128:131], v[12:15], v[88:91]
	v_mfma_f32_16x16x32_bf16 v[124:127], v[128:131], v[4:7], v[124:127]
	s_nop 4
	ds_read_b128 v[88:91], v241
	s_waitcnt lgkmcnt(0)
	v_mfma_f32_16x16x32_bf16 v[128:131], v[88:91], v[0:3], 0
	v_mfma_f32_16x16x32_bf16 v[88:91], v[88:91], v[8:11], 0
	v_mfma_f32_16x16x32_bf16 v[136:139], v[132:135], v[12:15], v[88:91]
	v_mfma_f32_16x16x32_bf16 v[128:131], v[132:135], v[4:7], v[128:131]
	s_nop 5
	ds_read_b128 v[88:91], v241 offset:2304
	s_waitcnt lgkmcnt(0)
	v_mfma_f32_16x16x32_bf16 v[132:135], v[88:91], v[0:3], 0
	v_mfma_f32_16x16x32_bf16 v[88:91], v[88:91], v[8:11], 0
	v_mfma_f32_16x16x32_bf16 v[132:135], v[144:147], v[4:7], v[132:135]
	v_mfma_f32_16x16x32_bf16 v[144:147], v[144:147], v[12:15], v[88:91]
	s_nop 5
	ds_read_b128 v[88:91], v241 offset:4608
	s_waitcnt lgkmcnt(0)
	v_mfma_f32_16x16x32_bf16 v[148:151], v[88:91], v[0:3], 0
	v_mfma_f32_16x16x32_bf16 v[88:91], v[88:91], v[8:11], 0
	v_mfma_f32_16x16x32_bf16 v[186:189], v[174:177], v[4:7], v[148:151]
	v_mfma_f32_16x16x32_bf16 v[148:151], v[174:177], v[12:15], v[88:91]
	v_max3_f32 v174, v140, s49, v141
	v_max3_f32 v174, v174, v142, v143
	v_max3_f32 v174, v174, v136, v137
	s_nop 2
	v_max3_f32 v88, v124, s49, v125
	v_max3_f32 v88, v88, v126, v127
	v_max3_f32 v88, v88, v128, v129
	v_max3_f32 v88, v88, v130, v131
	v_max3_f32 v174, v174, v138, v139
	v_max3_f32 v88, v88, v132, v133
	v_max3_f32 v174, v174, v144, v145
	v_max3_f32 v88, v88, v134, v135
	v_max3_f32 v174, v174, v146, v147
	v_max3_f32 v88, v88, v186, v187
	v_max3_f32 v174, v174, v148, v149
	v_max3_f32 v88, v88, v188, v189
	v_max3_f32 v174, v174, v150, v151
	s_nop 1
	v_permlane32_swap_b32_e32 v88, v174
	v_max_f32_e32 v89, v88, v174
	v_mov_b32_e32 v175, v89
	s_nop 1
	v_permlane16_swap_b32_e32 v89, v175
	v_max_f32_e32 v89, v89, v175
	v_mov_b32_e32 v175, v89
	s_nop 1
	v_permlane32_swap_b32_e32 v89, v175
	v_max_f32_e32 v237, v239, v89
	v_max_f32_e32 v240, v238, v175
	v_sub_f32_e32 v89, v124, v237
	v_sub_f32_e32 v140, v140, v240
	v_exp_f32_e32 v192, v89
	v_sub_f32_e32 v89, v125, v237
	v_exp_f32_e32 v193, v140
	v_sub_f32_e32 v140, v141, v240
	v_exp_f32_e32 v194, v89
	v_sub_f32_e32 v89, v126, v237
	v_exp_f32_e32 v195, v140
	v_sub_f32_e32 v140, v142, v240
	v_exp_f32_e32 v196, v89
	v_sub_f32_e32 v89, v127, v237
	v_exp_f32_e32 v197, v140
	v_sub_f32_e32 v140, v143, v240
	v_sub_f32_e32 v136, v136, v240
	v_exp_f32_e32 v198, v89
	v_sub_f32_e32 v89, v128, v237
	v_exp_f32_e32 v199, v140
	v_exp_f32_e32 v201, v136
	v_sub_f32_e32 v136, v137, v240
	v_exp_f32_e32 v200, v89
	v_sub_f32_e32 v89, v129, v237
	v_exp_f32_e32 v203, v136
	v_pk_add_f32 v[136:137], v[192:193], 0 op_sel_hi:[1,0]
	v_exp_f32_e32 v202, v89
	v_sub_f32_e32 v89, v130, v237
	v_pk_add_f32 v[136:137], v[194:195], v[136:137]
	v_sub_f32_e32 v138, v138, v240
	v_exp_f32_e32 v204, v89
	v_sub_f32_e32 v89, v131, v237
	v_pk_add_f32 v[136:137], v[196:197], v[136:137]
	v_exp_f32_e32 v205, v138
	v_sub_f32_e32 v138, v139, v240
	v_exp_f32_e32 v206, v89
	v_sub_f32_e32 v89, v132, v237
	v_pk_add_f32 v[136:137], v[198:199], v[136:137]
	v_exp_f32_e32 v207, v138
	v_sub_f32_e32 v138, v144, v240
	v_exp_f32_e32 v176, v89
	v_sub_f32_e32 v89, v133, v237
	v_pk_add_f32 v[136:137], v[200:201], v[136:137]
	v_exp_f32_e32 v177, v138
	v_sub_f32_e32 v138, v145, v240
	v_exp_f32_e32 v178, v89
	v_sub_f32_e32 v89, v134, v237
	v_pk_add_f32 v[136:137], v[202:203], v[136:137]
	v_exp_f32_e32 v179, v138
	v_sub_f32_e32 v138, v146, v240
	v_cvt_pk_bf16_f32 v246, v200, v202
	v_lshlrev_b32_e32 v200, 1, v223
	v_sub_f32_e32 v88, v239, v237
	v_exp_f32_e32 v180, v89
	v_sub_f32_e32 v89, v135, v237
	v_exp_f32_e32 v181, v138
	v_sub_f32_e32 v138, v147, v240
	v_pk_add_f32 v[136:137], v[204:205], v[136:137]
	v_cvt_pk_bf16_f32 v245, v196, v198
	v_add3_u32 v196, v235, v231, v200
	v_exp_f32_e32 v182, v89
	v_sub_f32_e32 v89, v186, v237
	v_exp_f32_e32 v208, v88
	v_exp_f32_e32 v183, v138
	v_sub_f32_e32 v138, v148, v240
	v_pk_add_f32 v[136:137], v[206:207], v[136:137]
	v_cvt_pk_bf16_f32 v247, v204, v206
	v_add_u32_e32 v204, 0x2000, v196
	v_exp_f32_e32 v184, v89
	v_sub_f32_e32 v89, v187, v237
	v_exp_f32_e32 v185, v138
	v_sub_f32_e32 v138, v149, v240
	v_pk_add_f32 v[136:137], v[176:177], v[136:137]
	v_cvt_pk_bf16_f32 v244, v192, v194
	v_cvt_pk_bf16_f32 v192, v193, v195
	v_cvt_pk_bf16_f32 v193, v197, v199
	ds_read2_b64 v[196:199], v204 offset0:128 offset1:132
	v_exp_f32_e32 v186, v89
	v_sub_f32_e32 v89, v188, v237
	v_exp_f32_e32 v187, v138
	v_sub_f32_e32 v138, v150, v240
	v_pk_add_f32 v[136:137], v[178:179], v[136:137]
	v_exp_f32_e32 v188, v89
	v_sub_f32_e32 v89, v189, v237
	v_sub_f32_e32 v174, v238, v240
	v_exp_f32_e32 v189, v138
	v_sub_f32_e32 v138, v151, v240
	v_pk_add_f32 v[136:137], v[180:181], v[136:137]
	v_exp_f32_e32 v190, v89
	v_pk_mul_f32 v[134:135], v[86:87], v[208:209] op_sel_hi:[1,0]
	v_pk_mul_f32 v[132:133], v[84:85], v[208:209] op_sel_hi:[1,0]
	v_pk_mul_f32 v[130:131], v[82:83], v[208:209] op_sel_hi:[1,0]
	v_pk_mul_f32 v[128:129], v[80:81], v[208:209] op_sel_hi:[1,0]
	v_pk_mul_f32 v[126:127], v[78:79], v[208:209] op_sel_hi:[1,0]
	v_pk_mul_f32 v[124:125], v[76:77], v[208:209] op_sel_hi:[1,0]
	v_pk_mul_f32 v[90:91], v[74:75], v[208:209] op_sel_hi:[1,0]
	v_pk_mul_f32 v[88:89], v[72:73], v[208:209] op_sel_hi:[1,0]
	v_exp_f32_e32 v191, v138
	v_exp_f32_e32 v209, v174
	v_pk_add_f32 v[136:137], v[182:183], v[136:137]
	v_cvt_pk_bf16_f32 v195, v205, v207
	v_pk_add_f32 v[136:137], v[184:185], v[136:137]
	v_mov_b32_e32 v148, v209
	v_pk_add_f32 v[136:137], v[186:187], v[136:137]
	v_add3_u32 v205, v235, v236, v200
	v_pk_add_f32 v[136:137], v[188:189], v[136:137]
	v_pk_mul_f32 v[138:139], v[70:71], v[148:149] op_sel_hi:[1,0]
	v_pk_add_f32 v[136:137], v[190:191], v[136:137]
	v_cvt_pk_bf16_f32 v194, v201, v203
	v_pk_fma_f32 v[174:175], v[172:173], v[208:209], v[136:137]
	v_pk_mul_f32 v[136:137], v[68:69], v[148:149] op_sel_hi:[1,0]
	v_add_u32_e32 v206, 0x2000, v205
	s_waitcnt lgkmcnt(0)
; template <bool BOUNDARY, bool Q0, bool Q1>
; __device__ __forceinline__ void attn_tile(const bf16* Ks, const bf16* Vt, const bf16x8 (&Qf)[2][2], const uint32_t (&vm)[2],
;                                           float (&m)[2], float (&l)[2], f32x4 (&O)[4][2], int fr, int fq) {
;     ...
;     l[qt] = l[qt] * alpha + ls;
; #pragma unroll
;     for (int dt = 0; dt < 4; ++dt) {
;       O[dt][qt][0] *= alpha; O[dt][qt][1] *= alpha; O[dt][qt][2] *= alpha; O[dt][qt][3] *= alpha;
;     }
;   }
; #pragma unroll
;   for (int kp = 0; kp < 2; ++kp) {
;     bf16x8 Pf[2];
; #pragma unroll
;     for (int qt = 0; qt < 2; ++qt) {
;       const u32x4 pk = {pack2(S[2 * kp][qt][0], S[2 * kp][qt][1]), pack2(S[2 * kp][qt][2], S[2 * kp][qt][3]),
;                         pack2(S[2 * kp + 1][qt][0], S[2 * kp + 1][qt][1]), pack2(S[2 * kp + 1][qt][2], S[2 * kp + 1][qt][3])};
;       Pf[qt] = __builtin_bit_cast(bf16x8, pk);
;     }
; #pragma unroll
;     for (int dt = 0; dt < 4; ++dt) {
;       const bf16x4 v0 = *(const bf16x4*)(Vt + (16 * dt + fr) * VT_LD + 32 * kp + 4 * fq);
;       const bf16x4 v1 = *(const bf16x4*)(Vt + (16 * dt + fr) * VT_LD + 32 * kp + 16 + 4 * fq);
;       bf16x8 vf;
;       vf[0] = v0[0]; vf[1] = v0[1]; vf[2] = v0[2]; vf[3] = v0[3];
;       vf[4] = v1[0]; vf[5] = v1[1]; vf[6] = v1[2]; vf[7] = v1[3];
;       if (Q0) O[dt][0] = __builtin_amdgcn_mfma_f32_16x16x32_bf16(vf, Pf[0], O[dt][0], 0, 0, 0);
;       if (Q1) O[dt][1] = __builtin_amdgcn_mfma_f32_16x16x32_bf16(vf, Pf[1], O[dt][1], 0, 0, 0);
;     }
;   }
	v_mfma_f32_16x16x32_bf16 v[132:135], v[196:199], v[244:247], v[132:135]
	v_mul_f32_e64 v142, v66, v148
	v_mul_f32_e64 v143, v67, v148
	v_pk_mul_f32 v[140:141], v[64:65], v[148:149] op_sel_hi:[1,0]
	v_add_u32_e32 v207, 0x2800, v205
	v_mfma_f32_16x16x32_bf16 v[136:139], v[196:199], v[192:195], v[136:139]
	ds_read2_b64 v[196:199], v206 offset0:128 offset1:132
	v_add_u32_e32 v205, 0x3000, v205
	v_pk_mul_f32 v[146:147], v[62:63], v[148:149] op_sel_hi:[1,0]
	s_waitcnt lgkmcnt(0)
	v_mfma_f32_16x16x32_bf16 v[128:131], v[196:199], v[244:247], v[128:131]
	v_mul_f32_e64 v144, v60, v148
	v_mul_f32_e64 v145, v61, v148
	v_pk_mul_f32 v[150:151], v[58:59], v[148:149] op_sel_hi:[1,0]
	v_pk_mul_f32 v[148:149], v[56:57], v[148:149] op_sel_hi:[1,0]
	v_mfma_f32_16x16x32_bf16 v[140:143], v[196:199], v[192:195], v[140:143]
	ds_read2_b64 v[196:199], v207 offset0:144 offset1:148
	s_waitcnt lgkmcnt(0)
	v_mfma_f32_16x16x32_bf16 v[200:203], v[196:199], v[244:247], v[124:127]
	s_nop 2
	ds_read2_b64 v[124:127], v205 offset0:160 offset1:164
	v_mfma_f32_16x16x32_bf16 v[144:147], v[196:199], v[192:195], v[144:147]
	s_waitcnt lgkmcnt(0)
	v_mfma_f32_16x16x32_bf16 v[196:199], v[124:127], v[244:247], v[88:91]
	s_nop 2
	ds_read2_b64 v[88:91], v204 offset0:136 offset1:140
	v_mfma_f32_16x16x32_bf16 v[192:195], v[124:127], v[192:195], v[148:151]
	s_nop 2
	v_cvt_pk_bf16_f32 v148, v176, v178
	v_cvt_pk_bf16_f32 v149, v180, v182
	v_cvt_pk_bf16_f32 v150, v184, v186
	v_cvt_pk_bf16_f32 v151, v188, v190
	v_cvt_pk_bf16_f32 v176, v177, v179
	v_cvt_pk_bf16_f32 v177, v181, v183
	v_cvt_pk_bf16_f32 v178, v185, v187
	v_cvt_pk_bf16_f32 v179, v189, v191
	s_waitcnt lgkmcnt(0)
	v_mfma_f32_16x16x32_bf16 v[124:127], v[88:91], v[148:151], v[132:135]
	v_mfma_f32_16x16x32_bf16 v[88:91], v[88:91], v[176:179], v[136:139]
	s_nop 2
	ds_read2_b64 v[136:139], v206 offset0:136 offset1:140
	s_waitcnt lgkmcnt(0)
	v_mfma_f32_16x16x32_bf16 v[132:135], v[136:139], v[148:151], v[128:131]
	v_mfma_f32_16x16x32_bf16 v[128:131], v[136:139], v[176:179], v[140:143]
	ds_read2_b64 v[136:139], v207 offset0:152 offset1:156
	s_waitcnt lgkmcnt(0)
	v_mfma_f32_16x16x32_bf16 v[140:143], v[136:139], v[148:151], v[200:203]
	v_mfma_f32_16x16x32_bf16 v[136:139], v[136:139], v[176:179], v[144:147]
	s_nop 2
	ds_read2_b64 v[144:147], v205 offset0:168 offset1:172
	s_waitcnt lgkmcnt(0)
	v_mfma_f32_16x16x32_bf16 v[148:151], v[144:147], v[148:151], v[196:199]
	v_mfma_f32_16x16x32_bf16 v[144:147], v[144:147], v[176:179], v[192:195]
	s_cbranch_execz .LBB0_694
